# sample-group pooling history loads (30 dependent f32x4 loads) issued together instead of one latency each
# speedup vs baseline: 1.0093x; 1.0008x over previous
.LBB0_972:
	s_and_b64 vcc, exec, s[14:15]
	s_cbranch_vccz .LBB0_938
	s_add_i32 s14, s20, 0xffff8000
	s_lshr_b32 s14, s14, 4
	s_mul_i32 s18, s14, 15
	s_lshl_b64 s[14:15], s[18:19], 11
	v_lshl_add_u64 v[122:123], v[142:143], 0, s[14:15]
	s_mov_b32 s98, 0x7000
	s_mov_b32 s99, 0x0
	v_lshl_add_u64 v[156:157], v[122:123], 0, s[98:99]
	s_nop 1
	global_load_dwordx4 v[144:147], v[156:157], off
	global_load_dwordx4 v[148:151], v[156:157], off offset:16
	global_load_dwordx4 v[152:155], v[156:157], off offset:-2048
	global_load_dwordx4 v[162:165], v[156:157], off offset:-2032
	global_load_dwordx4 v[166:169], v[156:157], off offset:-4096
	global_load_dwordx4 v[170:173], v[156:157], off offset:-4080
	s_mov_b32 s98, 0x5800
	s_mov_b32 s99, 0x0
	v_lshl_add_u64 v[156:157], v[122:123], 0, s[98:99]
	s_nop 1
	global_load_dwordx4 v[174:177], v[156:157], off
	global_load_dwordx4 v[178:181], v[156:157], off offset:16
	global_load_dwordx4 v[182:185], v[156:157], off offset:-2048
	global_load_dwordx4 v[186:189], v[156:157], off offset:-2032
	global_load_dwordx4 v[190:193], v[156:157], off offset:-4096
	global_load_dwordx4 v[198:201], v[156:157], off offset:-4080
	s_mov_b32 s98, 0x4000
	s_mov_b32 s99, 0x0
	v_lshl_add_u64 v[156:157], v[122:123], 0, s[98:99]
	s_nop 1
	global_load_dwordx4 v[202:205], v[156:157], off
	global_load_dwordx4 v[206:209], v[156:157], off offset:16
	global_load_dwordx4 v[212:215], v[156:157], off offset:-2048
	global_load_dwordx4 v[220:223], v[156:157], off offset:-2032
	global_load_dwordx4 v[224:227], v[156:157], off offset:-4096
	global_load_dwordx4 v[228:231], v[156:157], off offset:-4080
	s_mov_b32 s98, 0x2800
	s_mov_b32 s99, 0x0
	v_lshl_add_u64 v[156:157], v[122:123], 0, s[98:99]
	s_nop 1
	global_load_dwordx4 v[232:235], v[156:157], off
	global_load_dwordx4 v[236:239], v[156:157], off offset:16
	global_load_dwordx4 v[240:243], v[156:157], off offset:-2048
	s_mov_b32 s98, 0x1000
	s_mov_b32 s99, 0x0
	v_lshl_add_u64 v[254:255], v[122:123], 0, s[98:99]
	s_nop 1
	s_waitcnt vmcnt(0)
	s_mov_b64 s[14:15], 0x7000
	v_add_co_u32_e32 v18, vcc, 0x7000, v122
	v_lshl_add_u64 v[46:47], v[122:123], 0, s[14:15]
	s_nop 0
	v_addc_co_u32_e32 v19, vcc, 0, v123, vcc
	v_mov_b32_e32 v18, v144
	v_mov_b32_e32 v19, v145
	v_mov_b32_e32 v20, v146
	v_mov_b32_e32 v21, v147
	global_load_dwordx4 v[144:147], v[156:157], off offset:-2032
	s_nop 0
	v_mov_b32_e32 v46, v148
	v_mov_b32_e32 v47, v149
	v_mov_b32_e32 v48, v150
	v_mov_b32_e32 v49, v151
	global_load_dwordx4 v[148:151], v[156:157], off offset:-4096
	s_mov_b64 s[14:15], 0x6800
	v_bfe_u32 v66, v18, 16, 1
	v_add3_u32 v18, v18, v66, s63
	v_bfe_u32 v66, v19, 16, 1
	v_lshrrev_b32_e32 v18, 16, v18
	v_add3_u32 v19, v19, v66, s63
	v_and_or_b32 v18, v19, s64, v18
	v_bfe_u32 v19, v20, 16, 1
	v_add3_u32 v19, v20, v19, s63
	v_bfe_u32 v20, v21, 16, 1
	v_lshrrev_b32_e32 v19, 16, v19
	v_add3_u32 v20, v21, v20, s63
	v_and_or_b32 v19, v20, s64, v19
	v_bfe_u32 v20, v46, 16, 1
	v_add3_u32 v20, v46, v20, s63
	v_bfe_u32 v21, v47, 16, 1
	v_lshrrev_b32_e32 v20, 16, v20
	v_add3_u32 v21, v47, v21, s63
	v_and_or_b32 v20, v21, s64, v20
	v_bfe_u32 v21, v48, 16, 1
	v_lshl_add_u64 v[66:67], v[122:123], 0, s[14:15]
	s_movk_i32 s14, 0x6000
	v_add3_u32 v21, v48, v21, s63
	v_bfe_u32 v46, v49, 16, 1
	v_add_co_u32_e32 v78, vcc, s14, v122
	v_lshrrev_b32_e32 v21, 16, v21
	v_add3_u32 v46, v49, v46, s63
	v_addc_co_u32_e32 v79, vcc, 0, v123, vcc
	v_and_or_b32 v21, v46, s64, v21
	v_mov_b32_e32 v46, v152
	v_mov_b32_e32 v47, v153
	v_mov_b32_e32 v48, v154
	v_mov_b32_e32 v49, v155
	global_load_dwordx4 v[152:155], v[156:157], off offset:-4080
	s_nop 0
	v_mov_b32_e32 v66, v162
	v_mov_b32_e32 v67, v163
	v_mov_b32_e32 v68, v164
	v_mov_b32_e32 v69, v165
	global_load_dwordx4 v[162:165], v[254:255], off
	v_add_co_u32_e32 v86, vcc, s65, v122
	s_movk_i32 s14, 0x3000
	s_nop 0
	v_addc_co_u32_e32 v87, vcc, 0, v123, vcc
	v_bfe_u32 v80, v46, 16, 1
	v_add3_u32 v46, v46, v80, s63
	v_bfe_u32 v80, v47, 16, 1
	v_lshrrev_b32_e32 v46, 16, v46
	v_add3_u32 v47, v47, v80, s63
	v_and_or_b32 v46, v47, s64, v46
	v_bfe_u32 v47, v48, 16, 1
	v_add3_u32 v47, v48, v47, s63
	v_bfe_u32 v48, v49, 16, 1
	v_lshrrev_b32_e32 v47, 16, v47
	v_add3_u32 v48, v49, v48, s63
	v_and_or_b32 v47, v48, s64, v47
	v_bfe_u32 v48, v66, 16, 1
	v_add3_u32 v48, v66, v48, s63
	v_bfe_u32 v49, v67, 16, 1
	v_lshrrev_b32_e32 v48, 16, v48
	v_add3_u32 v49, v67, v49, s63
	v_and_or_b32 v48, v49, s64, v48
	v_bfe_u32 v49, v68, 16, 1
	v_add3_u32 v49, v68, v49, s63
	v_bfe_u32 v66, v69, 16, 1
	v_lshrrev_b32_e32 v49, 16, v49
	v_add3_u32 v66, v69, v66, s63
	v_lshl_add_u64 v[80:81], v[122:123], 0, s[22:23]
	v_and_or_b32 v49, v66, s64, v49
	v_mov_b32_e32 v66, v166
	v_mov_b32_e32 v67, v167
	v_mov_b32_e32 v68, v168
	v_mov_b32_e32 v69, v169
	global_load_dwordx4 v[166:169], v[254:255], off offset:16
	s_nop 0
	v_mov_b32_e32 v78, v170
	v_mov_b32_e32 v79, v171
	v_mov_b32_e32 v80, v172
	v_mov_b32_e32 v81, v173
	global_load_dwordx4 v[170:173], v[254:255], off offset:-2032
	v_bfe_u32 v82, v66, 16, 1
	v_add3_u32 v66, v66, v82, s63
	v_bfe_u32 v82, v67, 16, 1
	v_lshrrev_b32_e32 v66, 16, v66
	v_add3_u32 v67, v67, v82, s63
	v_and_or_b32 v66, v67, s64, v66
	v_bfe_u32 v67, v68, 16, 1
	v_add3_u32 v67, v68, v67, s63
	v_bfe_u32 v68, v69, 16, 1
	v_lshrrev_b32_e32 v67, 16, v67
	v_add3_u32 v68, v69, v68, s63
	v_and_or_b32 v67, v68, s64, v67
	v_bfe_u32 v68, v78, 16, 1
	v_add3_u32 v68, v78, v68, s63
	v_bfe_u32 v69, v79, 16, 1
	v_lshrrev_b32_e32 v68, 16, v68
	v_add3_u32 v69, v79, v69, s63
	v_and_or_b32 v68, v69, s64, v68
	v_bfe_u32 v69, v80, 16, 1
	v_add3_u32 v69, v80, v69, s63
	v_bfe_u32 v78, v81, 16, 1
	v_lshrrev_b32_e32 v69, 16, v69
	v_add3_u32 v78, v81, v78, s63
	v_lshl_add_u64 v[82:83], v[122:123], 0, s[24:25]
	v_and_or_b32 v69, v78, s64, v69
	v_mov_b32_e32 v78, v174
	v_mov_b32_e32 v79, v175
	v_mov_b32_e32 v80, v176
	v_mov_b32_e32 v81, v177
	global_load_dwordx4 v[174:177], v[254:255], off offset:-2048
	s_nop 0
	v_mov_b32_e32 v82, v178
	v_mov_b32_e32 v83, v179
	v_mov_b32_e32 v84, v180
	v_mov_b32_e32 v85, v181
	global_load_dwordx4 v[178:181], v[254:255], off offset:-4080
	v_bfe_u32 v88, v78, 16, 1
	v_add3_u32 v78, v78, v88, s63
	v_bfe_u32 v88, v79, 16, 1
	v_lshrrev_b32_e32 v78, 16, v78
	v_add3_u32 v79, v79, v88, s63
	v_and_or_b32 v78, v79, s64, v78
	v_bfe_u32 v79, v80, 16, 1
	v_add3_u32 v79, v80, v79, s63
	v_bfe_u32 v80, v81, 16, 1
	v_lshrrev_b32_e32 v79, 16, v79
	v_add3_u32 v80, v81, v80, s63
	v_and_or_b32 v79, v80, s64, v79
	v_bfe_u32 v80, v82, 16, 1
	v_add3_u32 v80, v82, v80, s63
	v_bfe_u32 v81, v83, 16, 1
	v_lshrrev_b32_e32 v80, 16, v80
	v_add3_u32 v81, v83, v81, s63
	v_and_or_b32 v80, v81, s64, v80
	v_bfe_u32 v81, v84, 16, 1
	v_add3_u32 v81, v84, v81, s63
	v_bfe_u32 v82, v85, 16, 1
	v_lshrrev_b32_e32 v81, 16, v81
	v_add3_u32 v82, v85, v82, s63
	v_lshl_add_u64 v[88:89], v[122:123], 0, s[26:27]
	v_and_or_b32 v81, v82, s64, v81
	v_mov_b32_e32 v82, v182
	v_mov_b32_e32 v83, v183
	v_mov_b32_e32 v84, v184
	v_mov_b32_e32 v85, v185
	global_load_dwordx4 v[182:185], v[254:255], off offset:-4096
	s_nop 0
	v_mov_b32_e32 v86, v186
	v_mov_b32_e32 v87, v187
	v_mov_b32_e32 v88, v188
	v_mov_b32_e32 v89, v189
	v_bfe_u32 v90, v82, 16, 1
	v_add3_u32 v82, v82, v90, s63
	v_bfe_u32 v90, v83, 16, 1
	v_lshrrev_b32_e32 v82, 16, v82
	v_add3_u32 v83, v83, v90, s63
	v_and_or_b32 v82, v83, s64, v82
	v_bfe_u32 v83, v84, 16, 1
	v_add3_u32 v83, v84, v83, s63
	v_bfe_u32 v84, v85, 16, 1
	v_lshrrev_b32_e32 v83, 16, v83
	v_add3_u32 v84, v85, v84, s63
	v_and_or_b32 v83, v84, s64, v83
	v_bfe_u32 v84, v86, 16, 1
	v_add3_u32 v84, v86, v84, s63
	v_bfe_u32 v85, v87, 16, 1
	v_lshrrev_b32_e32 v84, 16, v84
	v_add3_u32 v85, v87, v85, s63
	v_and_or_b32 v84, v85, s64, v84
	v_bfe_u32 v85, v88, 16, 1
	v_add3_u32 v85, v88, v85, s63
	v_bfe_u32 v86, v89, 16, 1
	v_add_co_u32_e32 v90, vcc, s68, v122
	v_lshrrev_b32_e32 v85, 16, v85
	v_add3_u32 v86, v89, v86, s63
	v_addc_co_u32_e32 v91, vcc, 0, v123, vcc
	v_and_or_b32 v85, v86, s64, v85
	v_lshl_add_u64 v[86:87], v[122:123], 0, s[28:29]
	v_mov_b32_e32 v92, v190
	v_mov_b32_e32 v93, v191
	v_mov_b32_e32 v94, v192
	v_mov_b32_e32 v95, v193
	v_mov_b32_e32 v96, v198
	v_mov_b32_e32 v97, v199
	v_mov_b32_e32 v98, v200
	v_mov_b32_e32 v99, v201
	v_add_co_u32_e32 v102, vcc, s14, v122
	s_movk_i32 s14, 0x2000
	s_nop 0
	v_addc_co_u32_e32 v103, vcc, 0, v123, vcc
	v_add_co_u32_e32 v110, vcc, s14, v122
	s_movk_i32 s14, 0x1000
	s_nop 0
	v_addc_co_u32_e32 v111, vcc, 0, v123, vcc
	v_add_co_u32_e32 v118, vcc, s14, v122
	v_bfe_u32 v86, v92, 16, 1
	v_add3_u32 v86, v92, v86, s63
	v_bfe_u32 v87, v93, 16, 1
	v_lshrrev_b32_e32 v86, 16, v86
	v_add3_u32 v87, v93, v87, s63
	v_and_or_b32 v86, v87, s64, v86
	v_bfe_u32 v87, v94, 16, 1
	v_add3_u32 v87, v94, v87, s63
	v_bfe_u32 v88, v95, 16, 1
	v_lshrrev_b32_e32 v87, 16, v87
	v_add3_u32 v88, v95, v88, s63
	v_and_or_b32 v87, v88, s64, v87
	v_bfe_u32 v88, v96, 16, 1
	v_add3_u32 v88, v96, v88, s63
	v_bfe_u32 v89, v97, 16, 1
	v_lshrrev_b32_e32 v88, 16, v88
	v_add3_u32 v89, v97, v89, s63
	v_and_or_b32 v88, v89, s64, v88
	v_bfe_u32 v89, v98, 16, 1
	v_add3_u32 v89, v98, v89, s63
	v_bfe_u32 v92, v99, 16, 1
	v_lshrrev_b32_e32 v89, 16, v89
	v_add3_u32 v92, v99, v92, s63
	v_lshl_add_u64 v[94:95], v[122:123], 0, s[30:31]
	v_and_or_b32 v89, v92, s64, v89
	v_mov_b32_e32 v90, v202
	v_mov_b32_e32 v91, v203
	v_mov_b32_e32 v92, v204
	v_mov_b32_e32 v93, v205
	s_nop 0
	v_mov_b32_e32 v94, v206
	v_mov_b32_e32 v95, v207
	v_mov_b32_e32 v96, v208
	v_mov_b32_e32 v97, v209
	v_addc_co_u32_e32 v119, vcc, 0, v123, vcc
	v_bfe_u32 v98, v90, 16, 1
	v_add3_u32 v90, v90, v98, s63
	v_bfe_u32 v98, v91, 16, 1
	v_lshrrev_b32_e32 v90, 16, v90
	v_add3_u32 v91, v91, v98, s63
	v_and_or_b32 v90, v91, s64, v90
	v_bfe_u32 v91, v92, 16, 1
	v_add3_u32 v91, v92, v91, s63
	v_bfe_u32 v92, v93, 16, 1
	v_lshrrev_b32_e32 v91, 16, v91
	v_add3_u32 v92, v93, v92, s63
	v_and_or_b32 v91, v92, s64, v91
	v_bfe_u32 v92, v94, 16, 1
	v_add3_u32 v92, v94, v92, s63
	v_bfe_u32 v93, v95, 16, 1
	v_lshrrev_b32_e32 v92, 16, v92
	v_add3_u32 v93, v95, v93, s63
	v_and_or_b32 v92, v93, s64, v92
	v_bfe_u32 v93, v96, 16, 1
	v_add3_u32 v93, v96, v93, s63
	v_bfe_u32 v94, v97, 16, 1
	v_lshrrev_b32_e32 v93, 16, v93
	v_add3_u32 v94, v97, v94, s63
	v_lshl_add_u64 v[98:99], v[122:123], 0, s[38:39]
	v_and_or_b32 v93, v94, s64, v93
	v_mov_b32_e32 v94, v212
	v_mov_b32_e32 v95, v213
	v_mov_b32_e32 v96, v214
	v_mov_b32_e32 v97, v215
	s_nop 0
	v_mov_b32_e32 v98, v220
	v_mov_b32_e32 v99, v221
	v_mov_b32_e32 v100, v222
	v_mov_b32_e32 v101, v223
	v_bfe_u32 v104, v94, 16, 1
	v_add3_u32 v94, v94, v104, s63
	v_bfe_u32 v104, v95, 16, 1
	v_lshrrev_b32_e32 v94, 16, v94
	v_add3_u32 v95, v95, v104, s63
	v_and_or_b32 v94, v95, s64, v94
	v_bfe_u32 v95, v96, 16, 1
	v_add3_u32 v95, v96, v95, s63
	v_bfe_u32 v96, v97, 16, 1
	v_lshrrev_b32_e32 v95, 16, v95
	v_add3_u32 v96, v97, v96, s63
	v_and_or_b32 v95, v96, s64, v95
	v_bfe_u32 v96, v98, 16, 1
	v_add3_u32 v96, v98, v96, s63
	v_bfe_u32 v97, v99, 16, 1
	v_lshrrev_b32_e32 v96, 16, v96
	v_add3_u32 v97, v99, v97, s63
	v_and_or_b32 v96, v97, s64, v96
	v_bfe_u32 v97, v100, 16, 1
	v_add3_u32 v97, v100, v97, s63
	v_bfe_u32 v98, v101, 16, 1
	v_lshrrev_b32_e32 v97, 16, v97
	v_add3_u32 v98, v101, v98, s63
	v_lshl_add_u64 v[104:105], v[122:123], 0, s[40:41]
	v_and_or_b32 v97, v98, s64, v97
	v_mov_b32_e32 v98, v224
	v_mov_b32_e32 v99, v225
	v_mov_b32_e32 v100, v226
	v_mov_b32_e32 v101, v227
	s_nop 0
	v_mov_b32_e32 v102, v228
	v_mov_b32_e32 v103, v229
	v_mov_b32_e32 v104, v230
	v_mov_b32_e32 v105, v231
	v_bfe_u32 v106, v98, 16, 1
	v_add3_u32 v98, v98, v106, s63
	v_bfe_u32 v106, v99, 16, 1
	v_lshrrev_b32_e32 v98, 16, v98
	v_add3_u32 v99, v99, v106, s63
	v_and_or_b32 v98, v99, s64, v98
	v_bfe_u32 v99, v100, 16, 1
	v_add3_u32 v99, v100, v99, s63
	v_bfe_u32 v100, v101, 16, 1
	v_lshrrev_b32_e32 v99, 16, v99
	v_add3_u32 v100, v101, v100, s63
	v_and_or_b32 v99, v100, s64, v99
	v_bfe_u32 v100, v102, 16, 1
	v_add3_u32 v100, v102, v100, s63
	v_bfe_u32 v101, v103, 16, 1
	v_lshrrev_b32_e32 v100, 16, v100
	v_add3_u32 v101, v103, v101, s63
	v_and_or_b32 v100, v101, s64, v100
	v_bfe_u32 v101, v104, 16, 1
	v_add3_u32 v101, v104, v101, s63
	v_bfe_u32 v102, v105, 16, 1
	v_lshrrev_b32_e32 v101, 16, v101
	v_add3_u32 v102, v105, v102, s63
	v_lshl_add_u64 v[106:107], v[122:123], 0, s[42:43]
	v_and_or_b32 v101, v102, s64, v101
	v_mov_b32_e32 v102, v232
	v_mov_b32_e32 v103, v233
	v_mov_b32_e32 v104, v234
	v_mov_b32_e32 v105, v235
	s_nop 0
	v_mov_b32_e32 v106, v236
	v_mov_b32_e32 v107, v237
	v_mov_b32_e32 v108, v238
	v_mov_b32_e32 v109, v239
	v_bfe_u32 v112, v102, 16, 1
	v_add3_u32 v102, v102, v112, s63
	v_bfe_u32 v112, v103, 16, 1
	v_lshrrev_b32_e32 v102, 16, v102
	v_add3_u32 v103, v103, v112, s63
	v_and_or_b32 v102, v103, s64, v102
	v_bfe_u32 v103, v104, 16, 1
	v_add3_u32 v103, v104, v103, s63
	v_bfe_u32 v104, v105, 16, 1
	v_lshrrev_b32_e32 v103, 16, v103
	v_add3_u32 v104, v105, v104, s63
	v_and_or_b32 v103, v104, s64, v103
	v_bfe_u32 v104, v106, 16, 1
	v_add3_u32 v104, v106, v104, s63
	v_bfe_u32 v105, v107, 16, 1
	v_lshrrev_b32_e32 v104, 16, v104
	v_add3_u32 v105, v107, v105, s63
	v_and_or_b32 v104, v105, s64, v104
	v_bfe_u32 v105, v108, 16, 1
	v_add3_u32 v105, v108, v105, s63
	v_bfe_u32 v106, v109, 16, 1
	v_lshrrev_b32_e32 v105, 16, v105
	v_add3_u32 v106, v109, v106, s63
	v_lshl_add_u64 v[112:113], v[122:123], 0, s[48:49]
	v_and_or_b32 v105, v106, s64, v105
	v_mov_b32_e32 v106, v240
	v_mov_b32_e32 v107, v241
	v_mov_b32_e32 v108, v242
	v_mov_b32_e32 v109, v243
	s_nop 0
	s_waitcnt vmcnt(8)
	v_mov_b32_e32 v110, v144
	v_mov_b32_e32 v111, v145
	v_mov_b32_e32 v112, v146
	v_mov_b32_e32 v113, v147
	v_bfe_u32 v114, v106, 16, 1
	v_add3_u32 v106, v106, v114, s63
	v_bfe_u32 v114, v107, 16, 1
	v_lshrrev_b32_e32 v106, 16, v106
	v_add3_u32 v107, v107, v114, s63
	v_and_or_b32 v106, v107, s64, v106
	v_bfe_u32 v107, v108, 16, 1
	v_add3_u32 v107, v108, v107, s63
	v_bfe_u32 v108, v109, 16, 1
	v_lshrrev_b32_e32 v107, 16, v107
	v_add3_u32 v108, v109, v108, s63
	v_and_or_b32 v107, v108, s64, v107
	v_bfe_u32 v108, v110, 16, 1
	v_add3_u32 v108, v110, v108, s63
	v_bfe_u32 v109, v111, 16, 1
	v_lshrrev_b32_e32 v108, 16, v108
	v_add3_u32 v109, v111, v109, s63
	v_and_or_b32 v108, v109, s64, v108
	v_bfe_u32 v109, v112, 16, 1
	v_add3_u32 v109, v112, v109, s63
	v_bfe_u32 v110, v113, 16, 1
	v_lshrrev_b32_e32 v109, 16, v109
	v_add3_u32 v110, v113, v110, s63
	v_lshl_add_u64 v[114:115], v[122:123], 0, s[50:51]
	v_and_or_b32 v109, v110, s64, v109
	s_waitcnt vmcnt(7)
	v_mov_b32_e32 v110, v148
	v_mov_b32_e32 v111, v149
	v_mov_b32_e32 v112, v150
	v_mov_b32_e32 v113, v151
	s_nop 0
	s_waitcnt vmcnt(6)
	v_mov_b32_e32 v114, v152
	v_mov_b32_e32 v115, v153
	v_mov_b32_e32 v116, v154
	v_mov_b32_e32 v117, v155
	v_bfe_u32 v120, v110, 16, 1
	v_add3_u32 v110, v110, v120, s63
	v_bfe_u32 v120, v111, 16, 1
	v_lshrrev_b32_e32 v110, 16, v110
	v_add3_u32 v111, v111, v120, s63
	v_and_or_b32 v110, v111, s64, v110
	v_bfe_u32 v111, v112, 16, 1
	v_add3_u32 v111, v112, v111, s63
	v_bfe_u32 v112, v113, 16, 1
	v_lshrrev_b32_e32 v111, 16, v111
	v_add3_u32 v112, v113, v112, s63
	v_and_or_b32 v111, v112, s64, v111
	v_bfe_u32 v112, v114, 16, 1
	v_add3_u32 v112, v114, v112, s63
	v_bfe_u32 v113, v115, 16, 1
	v_lshrrev_b32_e32 v112, 16, v112
	v_add3_u32 v113, v115, v113, s63
	v_and_or_b32 v112, v113, s64, v112
	v_bfe_u32 v113, v116, 16, 1
	v_add3_u32 v113, v116, v113, s63
	v_bfe_u32 v114, v117, 16, 1
	v_lshrrev_b32_e32 v113, 16, v113
	v_add3_u32 v114, v117, v114, s63
	v_lshl_add_u64 v[120:121], v[122:123], 0, s[52:53]
	v_and_or_b32 v113, v114, s64, v113
	s_waitcnt vmcnt(5)
	v_mov_b32_e32 v114, v162
	v_mov_b32_e32 v115, v163
	v_mov_b32_e32 v116, v164
	v_mov_b32_e32 v117, v165
	s_nop 0
	s_waitcnt vmcnt(4)
	v_mov_b32_e32 v118, v166
	v_mov_b32_e32 v119, v167
	v_mov_b32_e32 v120, v168
	v_mov_b32_e32 v121, v169
	v_bfe_u32 v124, v114, 16, 1
	v_add3_u32 v114, v114, v124, s63
	v_bfe_u32 v124, v115, 16, 1
	v_lshrrev_b32_e32 v114, 16, v114
	v_add3_u32 v115, v115, v124, s63
	v_and_or_b32 v114, v115, s64, v114
	v_bfe_u32 v115, v116, 16, 1
	v_add3_u32 v115, v116, v115, s63
	v_bfe_u32 v116, v117, 16, 1
	v_lshrrev_b32_e32 v115, 16, v115
	v_add3_u32 v116, v117, v116, s63
	v_and_or_b32 v115, v116, s64, v115
	v_bfe_u32 v116, v118, 16, 1
	v_add3_u32 v116, v118, v116, s63
	v_bfe_u32 v117, v119, 16, 1
	v_lshrrev_b32_e32 v116, 16, v116
	v_add3_u32 v117, v119, v117, s63
	v_and_or_b32 v116, v117, s64, v116
	v_bfe_u32 v117, v120, 16, 1
	v_add3_u32 v117, v120, v117, s63
	v_bfe_u32 v118, v121, 16, 1
	v_lshrrev_b32_e32 v117, 16, v117
	v_add3_u32 v118, v121, v118, s63
	v_and_or_b32 v117, v118, s64, v117
	s_waitcnt vmcnt(3)
	v_mov_b32_e32 v124, v170
	v_mov_b32_e32 v125, v171
	v_mov_b32_e32 v126, v172
	v_mov_b32_e32 v127, v173
	s_waitcnt vmcnt(2)
	v_mov_b32_e32 v118, v174
	v_mov_b32_e32 v119, v175
	v_mov_b32_e32 v120, v176
	v_mov_b32_e32 v121, v177
	v_bfe_u32 v128, v118, 16, 1
	v_add3_u32 v118, v118, v128, s63
	v_bfe_u32 v128, v119, 16, 1
	v_lshrrev_b32_e32 v118, 16, v118
	v_add3_u32 v119, v119, v128, s63
	v_and_or_b32 v118, v119, s64, v118
	v_bfe_u32 v119, v120, 16, 1
	v_add3_u32 v119, v120, v119, s63
	v_bfe_u32 v120, v121, 16, 1
	v_lshrrev_b32_e32 v119, 16, v119
	v_add3_u32 v120, v121, v120, s63
	v_and_or_b32 v119, v120, s64, v119
	v_bfe_u32 v120, v124, 16, 1
	v_add3_u32 v120, v124, v120, s63
	v_bfe_u32 v121, v125, 16, 1
	v_lshrrev_b32_e32 v120, 16, v120
	v_add3_u32 v121, v125, v121, s63
	v_and_or_b32 v120, v121, s64, v120
	v_bfe_u32 v121, v126, 16, 1
	v_add3_u32 v121, v126, v121, s63
	v_bfe_u32 v124, v127, 16, 1
	v_lshrrev_b32_e32 v121, 16, v121
	v_add3_u32 v124, v127, v124, s63
	v_and_or_b32 v121, v124, s64, v121
	s_waitcnt vmcnt(1)
	v_mov_b32_e32 v124, v178
	v_mov_b32_e32 v125, v179
	v_mov_b32_e32 v126, v180
	v_mov_b32_e32 v127, v181
	s_waitcnt vmcnt(0)
	v_mov_b32_e32 v128, v182
	v_mov_b32_e32 v129, v183
	v_mov_b32_e32 v130, v184
	v_mov_b32_e32 v131, v185
	v_bfe_u32 v122, v128, 16, 1
	v_add3_u32 v122, v128, v122, s63
	v_bfe_u32 v123, v129, 16, 1
	v_lshrrev_b32_e32 v122, 16, v122
	v_add3_u32 v123, v129, v123, s63
	v_and_or_b32 v122, v123, s64, v122
	v_bfe_u32 v123, v130, 16, 1
	v_add3_u32 v123, v130, v123, s63
	v_bfe_u32 v128, v131, 16, 1
	v_lshrrev_b32_e32 v123, 16, v123
	v_add3_u32 v128, v131, v128, s63
	v_and_or_b32 v123, v128, s64, v123
	v_bfe_u32 v128, v124, 16, 1
	v_add3_u32 v124, v124, v128, s63
	v_bfe_u32 v128, v125, 16, 1
	v_lshrrev_b32_e32 v124, 16, v124
	v_add3_u32 v125, v125, v128, s63
	v_and_or_b32 v124, v125, s64, v124
	v_bfe_u32 v125, v126, 16, 1
	v_add3_u32 v125, v126, v125, s63
	v_bfe_u32 v126, v127, 16, 1
	v_lshrrev_b32_e32 v125, 16, v125
	v_add3_u32 v126, v127, v126, s63
	v_and_or_b32 v125, v126, s64, v125
	s_branch .LBB0_938
